# adds: P8 weight-transpose loop 1 uses counted vmcnt waits per item instead of one full drain per 3 items
# baseline (speedup 1.0000x reference)
; __device__ __forceinline__ void wt_load(f32x4 (&r)[8], const float* W, int N, int nblk, int item, int nitems, int lane) {
;     if (item < nitems) { const int kb = item / nblk, nb = item % nblk; const float* src = W + (size_t)(64 * kb + (lane >> 3)) * N + 32 * nb + (lane & 7) * 4;
; #pragma unroll
;         for (int i = 0; i < 8; ++i) r[i] = *(const f32x4*)(src + (size_t)(8 * i) * N); }
; }
; __device__ __forceinline__ void wt_matrix(const float* W, int K, int N, bf16* WT, int mode, int row_off, LAS float* scr, int gw, int NGW, int lane) {
;     ...
;     int item = gw;
;     wt_load(ra, W, N, nblk, item, nitems, lane); wt_load(rb, W, N, nblk, item + NGW, nitems, lane);
;     while (item < nitems) {
;         wt_load(rc, W, N, nblk, item + 2 * NGW, nitems, lane); wt_store(ra, K, nblk, WT, mode, row_off, scr, item, nitems, lane);
;         wt_load(ra, W, N, nblk, item + 3 * NGW, nitems, lane); wt_store(rb, K, nblk, WT, mode, row_off, scr, item + NGW, nitems, lane);
;         wt_load(rb, W, N, nblk, item + 4 * NGW, nitems, lane); wt_store(rc, K, nblk, WT, mode, row_off, scr, item + 2 * NGW, nitems, lane);
.LBB0_1069:
	s_add_i32 s22, s23, s14
	s_cmpk_lt_i32 s22, 0x1600
	s_cselect_b64 s[6:7], -1, 0
	s_cmpk_gt_i32 s22, 0x15ff
	s_cbranch_scc1 .Lw8a_skip
	s_ashr_i32 s24, s22, 31
	s_lshr_b32 s24, s24, 26
	s_add_i32 s24, s22, s24
	s_andn2_b32 s24, s24, 63
	v_or_b32_e32 v36, s24, v65
	s_sub_i32 s25, s22, s24
	v_ashrrev_i32_e32 v37, 31, v36
	v_lshlrev_b64 v[36:37], 13, v[36:37]
	s_lshl_b32 s24, s25, 5
	v_lshl_add_u64 v[36:37], s[88:89], 0, v[36:37]
	s_ashr_i32 s25, s24, 31
	v_lshl_add_u64 v[36:37], s[24:25], 2, v[36:37]
	v_lshlrev_b32_e32 v34, 2, v64
	v_lshl_add_u64 v[60:61], v[36:37], 0, v[34:35]
	v_add_co_u32_e32 v40, vcc, s17, v60
	s_nop 1
	v_addc_co_u32_e32 v41, vcc, 0, v61, vcc
	v_add_co_u32_e32 v44, vcc, s18, v60
	global_load_dwordx4 v[36:39], v[60:61], off
	s_nop 0
	global_load_dwordx4 v[40:43], v[40:41], off
	v_addc_co_u32_e32 v45, vcc, 0, v61, vcc
	v_add_co_u32_e32 v48, vcc, s19, v60
	s_nop 1
	v_addc_co_u32_e32 v49, vcc, 0, v61, vcc
	v_add_co_u32_e32 v52, vcc, 0x40000, v60
	global_load_dwordx4 v[44:47], v[44:45], off
	s_nop 0
	global_load_dwordx4 v[48:51], v[48:49], off
	v_addc_co_u32_e32 v53, vcc, 0, v61, vcc
	v_add_co_u32_e32 v56, vcc, 0x50000, v60
	s_nop 1
	v_addc_co_u32_e32 v57, vcc, 0, v61, vcc
	v_add_co_u32_e32 v62, vcc, 0x60000, v60
	global_load_dwordx4 v[52:55], v[52:53], off
	s_nop 0
	global_load_dwordx4 v[56:59], v[56:57], off
	v_addc_co_u32_e32 v63, vcc, 0, v61, vcc
	v_add_co_u32_e32 v98, vcc, 0x70000, v60
	s_nop 1
	v_addc_co_u32_e32 v99, vcc, 0, v61, vcc
	global_load_dwordx4 v[60:63], v[62:63], off
	s_nop 0
	global_load_dwordx4 v[98:101], v[98:99], off
	s_waitcnt vmcnt(16)
	s_branch .LBB0_1071

; #define LAS __attribute__((address_space(3)))
; __device__ __forceinline__ unsigned pk2(float lo, float hi) { f32x2 v = {lo, hi}; bf16x2_t b = __builtin_convertvector(v, bf16x2_t); return __builtin_bit_cast(unsigned, b); }
; __device__ __forceinline__ void wt_store(const f32x4 (&r)[8], int K, int nblk, bf16* WT, int mode, int row_off, LAS float* scr, int item, int nitems, int lane) {
;     if (item < nitems) {
;         const int kb = item / nblk, nb = item % nblk, k0 = 64 * kb, n0 = 32 * nb;
; #pragma unroll
;         for (int i = 0; i < 8; ++i) { LAS float* d = scr + (8 * i + (lane >> 3)) * 33 + (lane & 7) * 4; d[0] = r[i][0]; d[1] = r[i][1]; d[2] = r[i][2]; d[3] = r[i][3]; }
;         asm volatile("s_waitcnt lgkmcnt(0)" ::: "memory");
;         const int c = lane & 7;
; #pragma unroll
;         for (int j = 0; j < 4; ++j) { const int n = (lane >> 3) + 8 * j; const LAS float* s = scr + (8 * c) * 33 + n;
;             u32x4 o; o.x = pk2(s[0 * 33], s[1 * 33]); o.y = pk2(s[2 * 33], s[3 * 33]); o.z = pk2(s[4 * 33], s[5 * 33]); o.w = pk2(s[6 * 33], s[7 * 33]);
;             const int ng = n0 + n; int drow;
;             if (mode == 0) drow = row_off + ng; else drow = (ng >> 7) * 256 + (mode == 2 ? 128 : 0) + (ng & 127);
;             *(u32x4*)(WT + (size_t)drow * K + k0 + 8 * c) = o; }
;         asm volatile("s_waitcnt lgkmcnt(0)" ::: "memory");
;     }
; }
.LBB0_1071:
	s_ashr_i32 s24, s23, 31
	s_lshr_b32 s24, s24, 26
	v_add_u32_e32 v109, 0x420, v108
	v_add_u32_e32 v110, 0x428, v108
	v_add_u32_e32 v111, 0x840, v108
	v_add_u32_e32 v112, 0x848, v108
	v_add_u32_e32 v113, 0xc60, v108
	v_add_u32_e32 v114, 0xc68, v108
	v_add_u32_e32 v115, 0x1080, v108
	v_add_u32_e32 v116, 0x1088, v108
	v_add_u32_e32 v117, 0x14a0, v108
	v_add_u32_e32 v118, 0x14a8, v108
	v_add_u32_e32 v119, 0x18c0, v108
	v_add_u32_e32 v120, 0x18c8, v108
	v_add_u32_e32 v121, 0x1ce0, v108
	v_add_u32_e32 v122, 0x1ce8, v108
	s_add_i32 s24, s23, s24
	ds_write2_b32 v108, v2, v3 offset1:1
	ds_write2_b32 v108, v4, v5 offset0:2 offset1:3
	ds_write2_b32 v109, v6, v7 offset1:1
	ds_write2_b32 v110, v8, v9 offset1:1
	ds_write2_b32 v111, v10, v11 offset1:1
	ds_write2_b32 v112, v12, v13 offset1:1
	ds_write2_b32 v113, v14, v15 offset1:1
	ds_write2_b32 v114, v16, v17 offset1:1
	ds_write2_b32 v115, v18, v19 offset1:1
	ds_write2_b32 v116, v20, v21 offset1:1
	ds_write2_b32 v117, v22, v23 offset1:1
	ds_write2_b32 v118, v24, v25 offset1:1
	ds_write2_b32 v119, v26, v27 offset1:1
	ds_write2_b32 v120, v28, v29 offset1:1
	ds_write2_b32 v121, v30, v31 offset1:1
	ds_write2_b32 v122, v32, v33 offset1:1
	s_andn2_b32 s24, s24, 63
	s_waitcnt lgkmcnt(0)
	s_sub_i32 s25, s23, s24
	ds_read2_b32 v[130:131], v107 offset0:33 offset1:41
	ds_read2_b32 v[132:133], v107 offset1:8
	ds_read2_b32 v[134:135], v107 offset0:66 offset1:74
	ds_read2_b32 v[136:137], v107 offset0:99 offset1:107
	ds_read2_b32 v[138:139], v107 offset0:132 offset1:140
	ds_read2_b32 v[140:141], v107 offset0:165 offset1:173
	ds_read2_b32 v[142:143], v107 offset0:198 offset1:206
	ds_read2_b32 v[144:145], v107 offset0:231 offset1:239
	s_lshl_b32 s26, s25, 5
	v_or_b32_e32 v34, s26, v65
	s_ashr_i32 s25, s24, 31
	v_mul_lo_u32 v146, v34, s16
	v_lshl_add_u64 v[128:129], s[24:25], 1, v[102:103]
	v_ashrrev_i32_e32 v147, 31, v146
	v_or_b32_e32 v34, s26, v104
	s_waitcnt lgkmcnt(6)
	v_cvt_pk_bf16_f32 v124, v132, v130
	s_waitcnt lgkmcnt(4)
	v_cvt_pk_bf16_f32 v125, v134, v136
	s_waitcnt lgkmcnt(2)
	v_cvt_pk_bf16_f32 v126, v138, v140
	s_waitcnt lgkmcnt(0)
	v_cvt_pk_bf16_f32 v127, v142, v144
	v_lshl_add_u64 v[146:147], v[146:147], 1, v[128:129]
	v_mul_lo_u32 v130, v34, s16
	global_store_dwordx4 v[146:147], v[124:127], off
	v_or_b32_e32 v34, s26, v105
	v_mul_lo_u32 v146, v34, s16
	v_cvt_pk_bf16_f32 v124, v133, v131
	v_ashrrev_i32_e32 v131, 31, v130
	v_cvt_pk_bf16_f32 v125, v135, v137
	v_cvt_pk_bf16_f32 v126, v139, v141
	v_cvt_pk_bf16_f32 v127, v143, v145
	v_lshl_add_u64 v[130:131], v[130:131], 1, v[128:129]
	global_store_dwordx4 v[130:131], v[124:127], off
	ds_read2_b32 v[130:131], v107 offset0:49 offset1:57
	ds_read2_b32 v[132:133], v107 offset0:16 offset1:24
	ds_read2_b32 v[134:135], v107 offset0:82 offset1:90
	ds_read2_b32 v[136:137], v107 offset0:115 offset1:123
	ds_read2_b32 v[138:139], v107 offset0:148 offset1:156
	ds_read2_b32 v[140:141], v107 offset0:181 offset1:189
	ds_read2_b32 v[142:143], v107 offset0:214 offset1:222
	ds_read2_b32 v[144:145], v107 offset0:247 offset1:255
	v_ashrrev_i32_e32 v147, 31, v146
	v_or_b32_e32 v34, s26, v106
	s_waitcnt lgkmcnt(6)
	v_cvt_pk_bf16_f32 v124, v132, v130
	s_waitcnt lgkmcnt(4)
	v_cvt_pk_bf16_f32 v125, v134, v136
	s_waitcnt lgkmcnt(2)
	v_cvt_pk_bf16_f32 v126, v138, v140
	s_waitcnt lgkmcnt(0)
	v_cvt_pk_bf16_f32 v127, v142, v144
	v_lshl_add_u64 v[146:147], v[146:147], 1, v[128:129]
	v_mul_lo_u32 v130, v34, s16
	global_store_dwordx4 v[146:147], v[124:127], off
	s_add_i32 s24, s12, s23
	s_cmpk_gt_i32 s24, 0x15ff
	v_cvt_pk_bf16_f32 v124, v133, v131
	v_ashrrev_i32_e32 v131, 31, v130
	v_cvt_pk_bf16_f32 v125, v135, v137
	v_cvt_pk_bf16_f32 v126, v139, v141
	v_cvt_pk_bf16_f32 v127, v143, v145
	v_lshl_add_u64 v[128:129], v[130:131], 1, v[128:129]
	global_store_dwordx4 v[128:129], v[124:127], off
	s_waitcnt lgkmcnt(0)
	s_cbranch_scc1 .LBB0_1075
	s_ashr_i32 s25, s24, 31
	s_lshr_b32 s25, s25, 26
	s_add_i32 s25, s24, s25
	s_andn2_b32 s25, s25, 63
	v_or_b32_e32 v2, s25, v65
	s_sub_i32 s24, s24, s25
	v_ashrrev_i32_e32 v3, 31, v2
	v_lshlrev_b64 v[2:3], 13, v[2:3]
	s_lshl_b32 s24, s24, 5
	v_lshl_add_u64 v[2:3], s[88:89], 0, v[2:3]
	s_ashr_i32 s25, s24, 31
	v_lshl_add_u64 v[2:3], s[24:25], 2, v[2:3]
	v_lshlrev_b32_e32 v34, 2, v64
	v_lshl_add_u64 v[26:27], v[2:3], 0, v[34:35]
	v_add_co_u32_e32 v6, vcc, s17, v26
	s_mov_b32 s24, 0x40000
	s_nop 0
	v_addc_co_u32_e32 v7, vcc, 0, v27, vcc
	v_add_co_u32_e32 v10, vcc, s18, v26
	global_load_dwordx4 v[2:5], v[26:27], off
	s_nop 0
	global_load_dwordx4 v[6:9], v[6:7], off
	v_addc_co_u32_e32 v11, vcc, 0, v27, vcc
	v_add_co_u32_e32 v14, vcc, s19, v26
	s_nop 1
	v_addc_co_u32_e32 v15, vcc, 0, v27, vcc
	v_add_co_u32_e32 v18, vcc, s24, v26
	s_mov_b32 s24, 0x50000
	s_nop 0
	v_addc_co_u32_e32 v19, vcc, 0, v27, vcc
	v_add_co_u32_e32 v22, vcc, s24, v26
	global_load_dwordx4 v[10:13], v[10:11], off
	s_nop 0
	global_load_dwordx4 v[14:17], v[14:15], off
	v_addc_co_u32_e32 v23, vcc, 0, v27, vcc
	v_add_co_u32_e32 v28, vcc, s20, v26
	global_load_dwordx4 v[18:21], v[18:19], off
	s_nop 0
	global_load_dwordx4 v[22:25], v[22:23], off
	v_addc_co_u32_e32 v29, vcc, 0, v27, vcc
	v_add_co_u32_e32 v30, vcc, s21, v26
	s_nop 1
	v_addc_co_u32_e32 v31, vcc, 0, v27, vcc
	global_load_dwordx4 v[26:29], v[28:29], off
	s_nop 0
	global_load_dwordx4 v[30:33], v[30:31], off
	s_add_i32 s24, s2, s23
	s_cmpk_gt_i32 s24, 0x15ff
	s_cbranch_scc0 .Lw8a_rb

; __device__ __forceinline__ void wt_matrix(const float* W, int K, int N, bf16* WT, int mode, int row_off, LAS float* scr, int gw, int NGW, int lane) {
;     ...
;     while (item < nitems) {
;         wt_load(rc, W, N, nblk, item + 2 * NGW, nitems, lane); wt_store(ra, K, nblk, WT, mode, row_off, scr, item, nitems, lane);
;         wt_load(ra, W, N, nblk, item + 3 * NGW, nitems, lane); wt_store(rb, K, nblk, WT, mode, row_off, scr, item + NGW, nitems, lane);
;         wt_load(rb, W, N, nblk, item + 4 * NGW, nitems, lane); wt_store(rc, K, nblk, WT, mode, row_off, scr, item + 2 * NGW, nitems, lane);
;         item += 3 * NGW;
;     }
.LBB0_1074:
	s_ashr_i32 s24, s23, 31
	s_lshr_b32 s24, s24, 26
	s_add_i32 s24, s23, s24
	s_andn2_b32 s24, s24, 63
	v_or_b32_e32 v66, s24, v65
	s_sub_i32 s23, s23, s24
	v_ashrrev_i32_e32 v67, 31, v66
	v_lshlrev_b64 v[66:67], 13, v[66:67]
	s_lshl_b32 s24, s23, 5
	v_lshl_add_u64 v[66:67], s[88:89], 0, v[66:67]
	s_ashr_i32 s25, s24, 31
	v_lshl_add_u64 v[66:67], s[24:25], 2, v[66:67]
	v_lshlrev_b32_e32 v34, 2, v64
	v_lshl_add_u64 v[90:91], v[66:67], 0, v[34:35]
	v_add_co_u32_e32 v70, vcc, s17, v90
	s_nop 1
	v_addc_co_u32_e32 v71, vcc, 0, v91, vcc
	v_add_co_u32_e32 v74, vcc, s18, v90
	global_load_dwordx4 v[66:69], v[90:91], off
	s_nop 0
	global_load_dwordx4 v[70:73], v[70:71], off
	v_addc_co_u32_e32 v75, vcc, 0, v91, vcc
	v_add_co_u32_e32 v78, vcc, s19, v90
	s_nop 1
	v_addc_co_u32_e32 v79, vcc, 0, v91, vcc
	v_add_co_u32_e32 v82, vcc, 0x40000, v90
	global_load_dwordx4 v[74:77], v[74:75], off
	s_nop 0
	global_load_dwordx4 v[78:81], v[78:79], off
	v_addc_co_u32_e32 v83, vcc, 0, v91, vcc
	v_add_co_u32_e32 v86, vcc, 0x50000, v90
	s_nop 1
	v_addc_co_u32_e32 v87, vcc, 0, v91, vcc
	v_add_co_u32_e32 v92, vcc, 0x60000, v90
	global_load_dwordx4 v[82:85], v[82:83], off
	s_nop 0
	global_load_dwordx4 v[86:89], v[86:87], off
	v_addc_co_u32_e32 v93, vcc, 0, v91, vcc
	v_add_co_u32_e32 v90, vcc, 0x70000, v90
	s_nop 1
	v_addc_co_u32_e32 v91, vcc, 0, v91, vcc
	global_load_dwordx4 v[94:97], v[92:93], off
	s_nop 0
	global_load_dwordx4 v[90:93], v[90:91], off
	s_andn2_b64 vcc, exec, s[6:7]
	s_cbranch_vccnz .LBB0_1068
	s_waitcnt vmcnt(24)
	s_branch .LBB0_1078
.LBB0_1075:
	s_add_i32 s24, s2, s23
	s_cmpk_gt_i32 s24, 0x15ff
	s_cbranch_scc1 .LBB0_1073
	s_waitcnt vmcnt(0)
	s_branch .LBB0_1076
.Lw8a_rb:
	s_waitcnt vmcnt(20)

; __device__ __forceinline__ void wt_matrix(const float* W, int K, int N, bf16* WT, int mode, int row_off, LAS float* scr, int gw, int NGW, int lane) {
;     ...
;     while (item < nitems) {
;         wt_load(rc, W, N, nblk, item + 2 * NGW, nitems, lane); wt_store(ra, K, nblk, WT, mode, row_off, scr, item, nitems, lane);
;         wt_load(ra, W, N, nblk, item + 3 * NGW, nitems, lane); wt_store(rb, K, nblk, WT, mode, row_off, scr, item + NGW, nitems, lane);
;         wt_load(rb, W, N, nblk, item + 4 * NGW, nitems, lane); wt_store(rc, K, nblk, WT, mode, row_off, scr, item + 2 * NGW, nitems, lane);
;         item += 3 * NGW;
;     }
.LBB0_1077:
	s_andn2_b64 vcc, exec, s[6:7]
	s_cbranch_vccnz .LBB0_1068
	s_waitcnt vmcnt(0)
